# group barriers with nx==1: last arriver also skips the cross-XCD TOP/TOPGEN stage (in addition to the L2 write-back)
# baseline (speedup 1.0000x reference)
; __device__ __forceinline__ unsigned xb_ld(unsigned* p)              { return __hip_atomic_load(p, __ATOMIC_RELAXED, __HIP_MEMORY_SCOPE_AGENT); }
; __device__ __forceinline__ unsigned xb_add(unsigned* p, unsigned v) { return __hip_atomic_fetch_add(p, v, __ATOMIC_RELAXED, __HIP_MEMORY_SCOPE_AGENT); }
; #define XB_SPIN(cond, bar) do { unsigned _sp = 0; while (cond) { __builtin_amdgcn_s_sleep(1); \
;     if ((++_sp & 255u) == 0u) { if (xb_ld(&(bar)[XB_TMO])) break; if (_sp > XB_SPIN_CAP) { atomicAdd(&(bar)[XB_TMO], 1u); break; } } } } while (0)
; __device__ __forceinline__ void xcd_barrier(const XcdBarrier& b) {
;     ...
;         const unsigned old = xb_add(&bar[XB_XSUB(b.x)], 1u);
;         const unsigned gen = old / nloc;
;         if (old + 1u == (gen + 1u) * nloc) {
;             __builtin_amdgcn_fence(__ATOMIC_RELEASE, "agent");
;             asm volatile("s_waitcnt vmcnt(0)" ::: "memory");
;             const unsigned og = xb_add(&bar[XB_TOP], 1u);
;             const unsigned tg = og / nx;
;             if (og + 1u == (tg + 1u) * nx) xb_add(&bar[XB_TOPGEN], 1u);
;             else XB_SPIN(xb_ld(&bar[XB_TOPGEN]) == tg, bar);
;             __builtin_amdgcn_fence(__ATOMIC_ACQUIRE, "agent");
;             xb_add(&bar[XB_XGEN(b.x)], 1u);
;             asm volatile("s_waitcnt vmcnt(0)" ::: "memory");
.LBB0_675:
	s_andn2_saveexec_b64 s[2:3], s[2:3]
	s_cbranch_execz .LBB0_691
	v_readlane_b32 s2, v252, 44
	v_cmp_eq_u32_e32 vcc, 1, v3
	s_cbranch_vccnz .Lgb_fast0
	buffer_wbl2 sc1
	s_waitcnt lgkmcnt(0)
	s_waitcnt vmcnt(0)
	v_readlane_b32 s3, v252, 45
	v_cvt_f32_u32_e32 v4, v3
	v_sub_u32_e32 v5, 0, v3
	s_mov_b64 s[4:5], -1
	v_rcp_iflag_f32_e32 v4, v4
	s_nop 0
	global_atomic_add v2, v99, v215, s[2:3] sc0
	v_readlane_b32 s2, v252, 46
	v_readlane_b32 s3, v252, 47
	v_mul_f32_e32 v4, 0x4f7ffffe, v4
	v_cvt_u32_f32_e32 v4, v4
	v_mul_lo_u32 v5, v5, v4
	v_mul_hi_u32 v5, v4, v5
	v_add_u32_e32 v4, v4, v5
	s_waitcnt vmcnt(0)
	v_mul_hi_u32 v4, v2, v4
	v_mul_lo_u32 v5, v4, v3
	v_sub_u32_e32 v5, v2, v5
	v_cmp_ge_u32_e32 vcc, v5, v3
	v_add_u32_e32 v6, 1, v4
	v_add_u32_e32 v2, 1, v2
	v_cndmask_b32_e32 v4, v4, v6, vcc
	v_sub_u32_e32 v6, v5, v3
	v_cndmask_b32_e32 v5, v5, v6, vcc
	v_cmp_ge_u32_e32 vcc, v5, v3
	v_add_u32_e32 v5, 1, v4
	s_nop 0
	v_cndmask_b32_e32 v4, v4, v5, vcc
	v_mul_lo_u32 v5, v3, v4
	v_add_u32_e32 v3, v5, v3
	v_cmp_ne_u32_e32 vcc, v2, v3
	v_mov_b64_e32 v[2:3], s[2:3]
	s_and_saveexec_b64 s[2:3], vcc
	s_cbranch_execz .LBB0_688
	v_readlane_b32 s4, v252, 46
	v_readlane_b32 s5, v252, 47
	s_mov_b64 s[6:7], 0
	s_nop 3
	global_load_dword v2, v99, s[4:5] sc1
	s_waitcnt vmcnt(0)
	v_cmp_eq_u32_e32 vcc, v2, v4
	s_and_saveexec_b64 s[4:5], vcc
	s_cbranch_execz .LBB0_687
	s_mov_b32 s18, 1
	s_branch .LBB0_680

; __device__ __forceinline__ unsigned xb_add(unsigned* p, unsigned v) { return __hip_atomic_fetch_add(p, v, __ATOMIC_RELAXED, __HIP_MEMORY_SCOPE_AGENT); }
; __device__ __forceinline__ void xcd_barrier(const XcdBarrier& b) {
;     ...
;             __builtin_amdgcn_fence(__ATOMIC_ACQUIRE, "agent");
;             xb_add(&bar[XB_XGEN(b.x)], 1u);
;             asm volatile("s_waitcnt vmcnt(0)" ::: "memory");
.Lgb_fast0:
	v_readlane_b32 s2, v252, 42
	v_readlane_b32 s3, v252, 43
	s_waitcnt vmcnt(0)
	buffer_inv sc1
	s_nop 2
	global_atomic_add v99, v215, s[2:3]
	s_waitcnt vmcnt(0)

; __device__ __forceinline__ unsigned xb_ld(unsigned* p)              { return __hip_atomic_load(p, __ATOMIC_RELAXED, __HIP_MEMORY_SCOPE_AGENT); }
; __device__ __forceinline__ unsigned xb_add(unsigned* p, unsigned v) { return __hip_atomic_fetch_add(p, v, __ATOMIC_RELAXED, __HIP_MEMORY_SCOPE_AGENT); }
; #define XB_SPIN(cond, bar) do { unsigned _sp = 0; while (cond) { __builtin_amdgcn_s_sleep(1); \
;     if ((++_sp & 255u) == 0u) { if (xb_ld(&(bar)[XB_TMO])) break; if (_sp > XB_SPIN_CAP) { atomicAdd(&(bar)[XB_TMO], 1u); break; } } } } while (0)
; __device__ __forceinline__ void xcd_barrier(const XcdBarrier& b) {
;     ...
;         const unsigned old = xb_add(&bar[XB_XSUB(b.x)], 1u);
;         const unsigned gen = old / nloc;
;         if (old + 1u == (gen + 1u) * nloc) {
;             __builtin_amdgcn_fence(__ATOMIC_RELEASE, "agent");
;             asm volatile("s_waitcnt vmcnt(0)" ::: "memory");
;             const unsigned og = xb_add(&bar[XB_TOP], 1u);
;             const unsigned tg = og / nx;
;             if (og + 1u == (tg + 1u) * nx) xb_add(&bar[XB_TOPGEN], 1u);
;             else XB_SPIN(xb_ld(&bar[XB_TOPGEN]) == tg, bar);
.LBB0_1084:
	s_andn2_saveexec_b64 s[2:3], s[2:3]
	s_cbranch_execz .LBB0_1100
	v_readlane_b32 s2, v252, 44
	v_cmp_eq_u32_e32 vcc, 1, v3
	s_cbranch_vccnz .Lgb_fast4
	buffer_wbl2 sc1
	s_waitcnt lgkmcnt(0)
	s_waitcnt vmcnt(0)
	v_readlane_b32 s3, v252, 45
	v_cvt_f32_u32_e32 v4, v3
	v_sub_u32_e32 v5, 0, v3
	s_mov_b64 s[4:5], -1
	v_rcp_iflag_f32_e32 v4, v4
	s_nop 0
	global_atomic_add v2, v99, v215, s[2:3] sc0
	v_readlane_b32 s2, v252, 46
	v_readlane_b32 s3, v252, 47
	v_mul_f32_e32 v4, 0x4f7ffffe, v4
	v_cvt_u32_f32_e32 v4, v4
	v_mul_lo_u32 v5, v5, v4
	v_mul_hi_u32 v5, v4, v5
	v_add_u32_e32 v4, v4, v5
	s_waitcnt vmcnt(0)
	v_mul_hi_u32 v4, v2, v4
	v_mul_lo_u32 v5, v4, v3
	v_sub_u32_e32 v5, v2, v5
	v_cmp_ge_u32_e32 vcc, v5, v3
	v_add_u32_e32 v6, 1, v4
	v_add_u32_e32 v2, 1, v2
	v_cndmask_b32_e32 v4, v4, v6, vcc
	v_sub_u32_e32 v6, v5, v3
	v_cndmask_b32_e32 v5, v5, v6, vcc
	v_cmp_ge_u32_e32 vcc, v5, v3
	v_add_u32_e32 v5, 1, v4
	s_nop 0
	v_cndmask_b32_e32 v4, v4, v5, vcc
	v_mul_lo_u32 v5, v3, v4
	v_add_u32_e32 v3, v5, v3
	v_cmp_ne_u32_e32 vcc, v2, v3
	v_mov_b64_e32 v[2:3], s[2:3]
	s_and_saveexec_b64 s[2:3], vcc
	s_cbranch_execz .LBB0_1097
	v_readlane_b32 s4, v252, 46
	v_readlane_b32 s5, v252, 47
	s_mov_b64 s[8:9], 0
	s_nop 3
	global_load_dword v2, v99, s[4:5] sc1
	s_waitcnt vmcnt(0)
	v_cmp_eq_u32_e32 vcc, v2, v4
	s_and_saveexec_b64 s[4:5], vcc
	s_cbranch_execz .LBB0_1096
	s_mov_b32 s10, 1
	s_branch .LBB0_1089

; __device__ __forceinline__ unsigned xb_ld(unsigned* p)              { return __hip_atomic_load(p, __ATOMIC_RELAXED, __HIP_MEMORY_SCOPE_AGENT); }
; __device__ __forceinline__ unsigned xb_add(unsigned* p, unsigned v) { return __hip_atomic_fetch_add(p, v, __ATOMIC_RELAXED, __HIP_MEMORY_SCOPE_AGENT); }
; #define XB_SPIN(cond, bar) do { unsigned _sp = 0; while (cond) { __builtin_amdgcn_s_sleep(1); \
;     if ((++_sp & 255u) == 0u) { if (xb_ld(&(bar)[XB_TMO])) break; if (_sp > XB_SPIN_CAP) { atomicAdd(&(bar)[XB_TMO], 1u); break; } } } } while (0)
; __device__ __forceinline__ void xcd_barrier(const XcdBarrier& b) {
;     ...
;         const unsigned old = xb_add(&bar[XB_XSUB(b.x)], 1u);
;         const unsigned gen = old / nloc;
;         if (old + 1u == (gen + 1u) * nloc) {
;             __builtin_amdgcn_fence(__ATOMIC_RELEASE, "agent");
;             asm volatile("s_waitcnt vmcnt(0)" ::: "memory");
;             const unsigned og = xb_add(&bar[XB_TOP], 1u);
;             const unsigned tg = og / nx;
;             if (og + 1u == (tg + 1u) * nx) xb_add(&bar[XB_TOPGEN], 1u);
;             else XB_SPIN(xb_ld(&bar[XB_TOPGEN]) == tg, bar);
.LBB0_1131:
	s_andn2_saveexec_b64 s[4:5], s[4:5]
	s_cbranch_execz .LBB0_1147
	v_readlane_b32 s4, v252, 44
	v_cmp_eq_u32_e32 vcc, 1, v3
	s_cbranch_vccnz .Lgb_fast5
	buffer_wbl2 sc1
	s_waitcnt lgkmcnt(0)
	s_waitcnt vmcnt(0)
	v_readlane_b32 s5, v252, 45
	v_cvt_f32_u32_e32 v4, v3
	v_sub_u32_e32 v5, 0, v3
	s_mov_b64 s[6:7], -1
	v_rcp_iflag_f32_e32 v4, v4
	s_nop 0
	global_atomic_add v2, v99, v215, s[4:5] sc0
	v_readlane_b32 s4, v252, 46
	v_readlane_b32 s5, v252, 47
	v_mul_f32_e32 v4, 0x4f7ffffe, v4
	v_cvt_u32_f32_e32 v4, v4
	v_mul_lo_u32 v5, v5, v4
	v_mul_hi_u32 v5, v4, v5
	v_add_u32_e32 v4, v4, v5
	s_waitcnt vmcnt(0)
	v_mul_hi_u32 v4, v2, v4
	v_mul_lo_u32 v5, v4, v3
	v_sub_u32_e32 v5, v2, v5
	v_cmp_ge_u32_e32 vcc, v5, v3
	v_add_u32_e32 v6, 1, v4
	v_add_u32_e32 v2, 1, v2
	v_cndmask_b32_e32 v4, v4, v6, vcc
	v_sub_u32_e32 v6, v5, v3
	v_cndmask_b32_e32 v5, v5, v6, vcc
	v_cmp_ge_u32_e32 vcc, v5, v3
	v_add_u32_e32 v5, 1, v4
	s_nop 0
	v_cndmask_b32_e32 v4, v4, v5, vcc
	v_mul_lo_u32 v5, v3, v4
	v_add_u32_e32 v3, v5, v3
	v_cmp_ne_u32_e32 vcc, v2, v3
	v_mov_b64_e32 v[2:3], s[4:5]
	s_and_saveexec_b64 s[4:5], vcc
	s_cbranch_execz .LBB0_1144
	v_readlane_b32 s6, v252, 46
	v_readlane_b32 s7, v252, 47
	s_mov_b64 s[8:9], 0
	s_nop 3
	global_load_dword v2, v99, s[6:7] sc1
	s_waitcnt vmcnt(0)
	v_cmp_eq_u32_e32 vcc, v2, v4
	s_and_saveexec_b64 s[6:7], vcc
	s_cbranch_execz .LBB0_1143
	s_mov_b32 s20, 1
	s_branch .LBB0_1136

; __device__ __forceinline__ unsigned xb_add(unsigned* p, unsigned v) { return __hip_atomic_fetch_add(p, v, __ATOMIC_RELAXED, __HIP_MEMORY_SCOPE_AGENT); }
; __device__ __forceinline__ void xcd_barrier(const XcdBarrier& b) {
;     ...
;             __builtin_amdgcn_fence(__ATOMIC_ACQUIRE, "agent");
;             xb_add(&bar[XB_XGEN(b.x)], 1u);
;             asm volatile("s_waitcnt vmcnt(0)" ::: "memory");
.Lgb_fast5:
	v_readlane_b32 s4, v252, 42
	v_readlane_b32 s5, v252, 43
	s_waitcnt vmcnt(0)
	buffer_inv sc1
	s_nop 2
	global_atomic_add v99, v215, s[4:5]
	s_waitcnt vmcnt(0)
